# adds: MLA unit setup issues all rope-table loads up front (3 fewer serialized round trips), P0 gate-weight loop unrolled with all 16 loads in flight, FoX QK K-fragment and bias reads hoisted ahead of
# speedup vs baseline: 1.0043x; 1.0043x over previous
.LBB0_15:
	v_readlane_b32 s4, v236, 4
	v_readlane_b32 s5, v236, 5
	s_cmp_lt_i32 s4, 1
	s_cselect_b64 s[0:1], -1, 0
	s_cmp_gt_i32 s5, 0
	s_cselect_b64 s[4:5], -1, 0
	s_and_b64 s[0:1], s[0:1], s[4:5]
	s_andn2_b64 vcc, exec, s[0:1]
	s_cbranch_vccnz .LBB0_106
	v_mov_b32_e32 v44, v182
	s_movk_i32 s4, 0x1000
	s_nop 0
	v_readfirstlane_b32 s3, v44
	v_cmp_gt_i32_e32 vcc, s4, v44
	s_and_saveexec_b64 s[6:7], vcc
	s_cbranch_execz .LBB0_19
	v_lshlrev_b32_e32 v1, 2, v44
	s_movk_i32 s4, 0x3040
	s_waitcnt lgkmcnt(0)
	v_mov_b64_e32 v[2:3], s[58:59]
	v_mov_b32_e32 v5, 0
	v_ashrrev_i32_e32 v8, 2, v44
	v_and_b32_e32 v7, 12, v1
	v_mad_i64_i32 v[10:11], s[10:11], v8, s4, v[2:3]
	v_lshlrev_b32_e32 v4, 2, v7
	v_lshl_add_u64 v[10:11], v[10:11], 0, v[4:5]
	v_ashrrev_i32_e32 v9, 31, v8
	v_add_co_u32_e32 v10, vcc, 0x3000, v10
	v_lshl_add_u64 v[8:9], v[8:9], 2, s[54:55]
	s_nop 0
	v_addc_co_u32_e32 v11, vcc, 0, v11, vcc
	v_and_b32_e32 v12, -4, v44
	v_lshlrev_b32_e32 v7, 12, v7
	v_add3_u32 v7, 0, v7, v12
	s_mov_b32 s8, 0x182000
	s_mov_b32 s9, 0
	global_load_dword v48, v[8:9], off
	global_load_dwordx4 v[16:19], v[10:11], off
	v_lshl_add_u64 v[12:13], v[10:11], 0, s[8:9]
	global_load_dword v49, v[8:9], off offset:512
	global_load_dwordx4 v[20:23], v[12:13], off
	v_lshl_add_u64 v[12:13], v[12:13], 0, s[8:9]
	global_load_dword v50, v[8:9], off offset:1024
	global_load_dwordx4 v[24:27], v[12:13], off
	v_lshl_add_u64 v[12:13], v[12:13], 0, s[8:9]
	global_load_dword v51, v[8:9], off offset:1536
	global_load_dwordx4 v[28:31], v[12:13], off
	v_lshl_add_u64 v[12:13], v[12:13], 0, s[8:9]
	global_load_dword v52, v[8:9], off offset:2048
	global_load_dwordx4 v[32:35], v[12:13], off
	v_lshl_add_u64 v[12:13], v[12:13], 0, s[8:9]
	global_load_dword v53, v[8:9], off offset:2560
	global_load_dwordx4 v[36:39], v[12:13], off
	v_lshl_add_u64 v[12:13], v[12:13], 0, s[8:9]
	global_load_dword v54, v[8:9], off offset:3072
	global_load_dwordx4 v[40:43], v[12:13], off
	v_lshl_add_u64 v[12:13], v[12:13], 0, s[8:9]
	global_load_dword v55, v[8:9], off offset:3584
	global_load_dwordx4 v[56:59], v[12:13], off
	s_waitcnt vmcnt(14)
	v_mul_f32_e32 v16, v16, v48
	v_mul_f32_e32 v17, v17, v48
	v_mul_f32_e32 v18, v18, v48
	v_mul_f32_e32 v19, v19, v48
	ds_write2st64_b32 v7, v16, v17 offset0:0 offset1:16
	ds_write2st64_b32 v7, v18, v19 offset0:32 offset1:48
	s_waitcnt vmcnt(12)
	v_mul_f32_e32 v20, v20, v49
	v_mul_f32_e32 v21, v21, v49
	v_mul_f32_e32 v22, v22, v49
	v_mul_f32_e32 v23, v23, v49
	ds_write2st64_b32 v7, v20, v21 offset0:2 offset1:18
	ds_write2st64_b32 v7, v22, v23 offset0:34 offset1:50
	s_waitcnt vmcnt(10)
	v_mul_f32_e32 v24, v24, v50
	v_mul_f32_e32 v25, v25, v50
	v_mul_f32_e32 v26, v26, v50
	v_mul_f32_e32 v27, v27, v50
	ds_write2st64_b32 v7, v24, v25 offset0:4 offset1:20
	ds_write2st64_b32 v7, v26, v27 offset0:36 offset1:52
	s_waitcnt vmcnt(8)
	v_mul_f32_e32 v28, v28, v51
	v_mul_f32_e32 v29, v29, v51
	v_mul_f32_e32 v30, v30, v51
	v_mul_f32_e32 v31, v31, v51
	ds_write2st64_b32 v7, v28, v29 offset0:6 offset1:22
	ds_write2st64_b32 v7, v30, v31 offset0:38 offset1:54
	s_waitcnt vmcnt(6)
	v_mul_f32_e32 v32, v32, v52
	v_mul_f32_e32 v33, v33, v52
	v_mul_f32_e32 v34, v34, v52
	v_mul_f32_e32 v35, v35, v52
	ds_write2st64_b32 v7, v32, v33 offset0:8 offset1:24
	ds_write2st64_b32 v7, v34, v35 offset0:40 offset1:56
	s_waitcnt vmcnt(4)
	v_mul_f32_e32 v36, v36, v53
	v_mul_f32_e32 v37, v37, v53
	v_mul_f32_e32 v38, v38, v53
	v_mul_f32_e32 v39, v39, v53
	ds_write2st64_b32 v7, v36, v37 offset0:10 offset1:26
	ds_write2st64_b32 v7, v38, v39 offset0:42 offset1:58
	s_waitcnt vmcnt(2)
	v_mul_f32_e32 v40, v40, v54
	v_mul_f32_e32 v41, v41, v54
	v_mul_f32_e32 v42, v42, v54
	v_mul_f32_e32 v43, v43, v54
	ds_write2st64_b32 v7, v40, v41 offset0:12 offset1:28
	ds_write2st64_b32 v7, v42, v43 offset0:44 offset1:60
	s_waitcnt vmcnt(0)
	v_mul_f32_e32 v56, v56, v55
	v_mul_f32_e32 v57, v57, v55
	v_mul_f32_e32 v58, v58, v55
	v_mul_f32_e32 v59, v59, v55
	ds_write2st64_b32 v7, v56, v57 offset0:14 offset1:30
	ds_write2st64_b32 v7, v58, v59 offset0:46 offset1:62

.LBB0_364:
	s_cmp_lg_u32 0, -1
	s_cselect_b32 s0, 0, 0
	s_add_i32 s1, s0, s8
	s_add_i32 s1, s1, 0x8000
	s_mov_b32 s33, m0
	s_mov_b32 m0, s1
	s_nop 0
	global_load_lds_dwordx4 v[102:103], off
	s_mov_b32 m0, s33
	s_add_i32 s0, s9, s0
	s_mov_b32 s1, m0
	s_mov_b32 m0, s0
	s_nop 0
	global_load_lds_dwordx4 v[104:105], off
	s_mov_b32 m0, s1
	ds_read_b128 v[184:187], v115 offset:40960
	ds_read_b128 v[188:191], v115 offset:45056
	ds_read_b128 v[192:195], v116 offset:40960
	ds_read_b128 v[196:199], v116 offset:45056
	ds_read_b128 v[200:203], v117 offset:40960
	ds_read_b128 v[204:207], v117 offset:45056
	ds_read_b128 v[208:211], v118 offset:40960
	ds_read_b128 v[212:215], v118 offset:45056
	ds_read_b128 v[106:109], v113
	ds_read_b128 v[140:143], v113 offset:128
	ds_read_b128 v[144:147], v113 offset:32
	ds_read_b128 v[148:151], v113 offset:160
	s_waitcnt lgkmcnt(11)
	v_mfma_f32_32x32x16_bf16 v[68:83], v[184:187], v[96:99], v[36:51]
	s_waitcnt lgkmcnt(10)
	v_mfma_f32_32x32x16_bf16 v[52:67], v[188:191], v[96:99], v[36:51]
	s_waitcnt lgkmcnt(9)
	v_mfma_f32_32x32x16_bf16 v[68:83], v[192:195], v[92:95], v[68:83]
	s_waitcnt lgkmcnt(8)
	v_mfma_f32_32x32x16_bf16 v[52:67], v[196:199], v[92:95], v[52:67]
	s_waitcnt lgkmcnt(7)
	v_mfma_f32_32x32x16_bf16 v[68:83], v[200:203], v[88:91], v[68:83]
	s_waitcnt lgkmcnt(6)
	v_mfma_f32_32x32x16_bf16 v[52:67], v[204:207], v[88:91], v[52:67]
	s_waitcnt lgkmcnt(5)
	v_mfma_f32_32x32x16_bf16 v[68:83], v[208:211], v[84:87], v[68:83]
	s_waitcnt lgkmcnt(4)
	v_mfma_f32_32x32x16_bf16 v[52:67], v[212:215], v[84:87], v[52:67]
	s_nop 9
	s_sub_i32 s0, s29, 64
	s_cmp_le_i32 s0, s28
	s_waitcnt lgkmcnt(3)
	v_sub_f32_e32 v68, v68, v106
	s_waitcnt lgkmcnt(2)
	v_sub_f32_e32 v106, v52, v140
	v_sub_f32_e32 v69, v69, v107
	v_sub_f32_e32 v107, v53, v141
	v_sub_f32_e32 v52, v70, v108
	v_sub_f32_e32 v54, v54, v142
	v_sub_f32_e32 v53, v71, v109
	v_sub_f32_e32 v55, v55, v143
	s_waitcnt lgkmcnt(1)
	v_sub_f32_e32 v70, v72, v144
	s_waitcnt lgkmcnt(0)
	v_sub_f32_e32 v56, v56, v148
	v_sub_f32_e32 v71, v73, v145
	v_sub_f32_e32 v57, v57, v149
	v_sub_f32_e32 v72, v74, v146
	v_sub_f32_e32 v58, v58, v150
	ds_read_b128 v[140:143], v113 offset:64
	v_sub_f32_e32 v73, v75, v147
	ds_read_b128 v[144:147], v113 offset:192
	ds_read_b128 v[152:155], v113 offset:224
	v_sub_f32_e32 v59, v59, v151
	ds_read_b128 v[148:151], v113 offset:96
	s_waitcnt lgkmcnt(3)
	v_sub_f32_e32 v74, v76, v140
	s_waitcnt lgkmcnt(2)
	v_sub_f32_e32 v76, v60, v144
	v_sub_f32_e32 v75, v77, v141
	v_sub_f32_e32 v77, v61, v145
	v_sub_f32_e32 v60, v78, v142
	v_sub_f32_e32 v62, v62, v146
	v_sub_f32_e32 v61, v79, v143
	v_sub_f32_e32 v63, v63, v147
	s_waitcnt lgkmcnt(0)
	v_sub_f32_e32 v78, v80, v148
	v_sub_f32_e32 v64, v64, v152
	v_sub_f32_e32 v79, v81, v149
	v_sub_f32_e32 v65, v65, v153
	v_sub_f32_e32 v80, v82, v150
	v_sub_f32_e32 v66, v66, v154
	v_sub_f32_e32 v81, v83, v151
	v_sub_f32_e32 v67, v67, v155
	s_cbranch_scc1 .LBB0_366
	v_add_u32_e32 v82, 0x5b, v114
	v_cmp_lt_i32_e32 vcc, -1, v82
	s_nop 1
	v_cndmask_b32_e32 v68, v130, v68, vcc
	v_cmp_lt_i32_e32 vcc, 31, v82
	v_add_u32_e32 v82, 0x5a, v114
	s_nop 0
	v_cndmask_b32_e32 v106, v130, v106, vcc
	v_cmp_lt_i32_e32 vcc, -1, v82
	s_nop 1
	v_cndmask_b32_e32 v69, v130, v69, vcc
	v_cmp_lt_i32_e32 vcc, 31, v82
	v_add_u32_e32 v82, 0x59, v114
	s_nop 0
	v_cndmask_b32_e32 v107, v130, v107, vcc
	v_cmp_lt_i32_e32 vcc, -1, v82
	s_nop 1
	v_cndmask_b32_e32 v52, v130, v52, vcc
	v_cmp_lt_i32_e32 vcc, 31, v82
	v_add_u32_e32 v82, 0x58, v114
	s_nop 0
	v_cndmask_b32_e32 v54, v130, v54, vcc
	v_cmp_lt_i32_e32 vcc, -1, v82
	s_nop 1
	v_cndmask_b32_e32 v53, v130, v53, vcc
	v_cmp_lt_i32_e32 vcc, 31, v82
	v_add_u32_e32 v82, 0x53, v114
	s_nop 0
	v_cndmask_b32_e32 v55, v130, v55, vcc
	v_cmp_lt_i32_e32 vcc, -1, v82
	s_nop 1
	v_cndmask_b32_e32 v70, v130, v70, vcc
	v_cmp_lt_i32_e32 vcc, 31, v82
	v_add_u32_e32 v82, 0x52, v114
	s_nop 0
	v_cndmask_b32_e32 v56, v130, v56, vcc
	v_cmp_lt_i32_e32 vcc, -1, v82
	s_nop 1
	v_cndmask_b32_e32 v71, v130, v71, vcc
	v_cmp_lt_i32_e32 vcc, 31, v82
	v_add_u32_e32 v82, 0x51, v114
	s_nop 0
	v_cndmask_b32_e32 v57, v130, v57, vcc
	v_cmp_lt_i32_e32 vcc, -1, v82
	s_nop 1
	v_cndmask_b32_e32 v72, v130, v72, vcc
	v_cmp_lt_i32_e32 vcc, 31, v82
	v_add_u32_e32 v82, 0x50, v114
	s_nop 0
	v_cndmask_b32_e32 v58, v130, v58, vcc
	v_cmp_lt_i32_e32 vcc, -1, v82
	s_nop 1
	v_cndmask_b32_e32 v73, v130, v73, vcc
	v_cmp_lt_i32_e32 vcc, 31, v82
	v_add_u32_e32 v82, 0x4b, v114
	s_nop 0
	v_cndmask_b32_e32 v59, v130, v59, vcc
	v_cmp_lt_i32_e32 vcc, -1, v82
	s_nop 1
	v_cndmask_b32_e32 v74, v130, v74, vcc
	v_cmp_lt_i32_e32 vcc, 31, v82
	v_add_u32_e32 v82, 0x4a, v114
	s_nop 0
	v_cndmask_b32_e32 v76, v130, v76, vcc
	v_cmp_lt_i32_e32 vcc, -1, v82
	s_nop 1
	v_cndmask_b32_e32 v75, v130, v75, vcc
	v_cmp_lt_i32_e32 vcc, 31, v82
	v_add_u32_e32 v82, 0x49, v114
	s_nop 0
	v_cndmask_b32_e32 v77, v130, v77, vcc
	v_cmp_lt_i32_e32 vcc, -1, v82
	s_nop 1
	v_cndmask_b32_e32 v60, v130, v60, vcc
	v_cmp_lt_i32_e32 vcc, 31, v82
	v_add_u32_e32 v82, 0x48, v114
	s_nop 0
	v_cndmask_b32_e32 v62, v130, v62, vcc
	v_cmp_lt_i32_e32 vcc, -1, v82
	s_nop 1
	v_cndmask_b32_e32 v61, v130, v61, vcc
	v_cmp_lt_i32_e32 vcc, 31, v82
	v_add_u32_e32 v82, 0x43, v114
	s_nop 0
	v_cndmask_b32_e32 v63, v130, v63, vcc
	v_cmp_lt_i32_e32 vcc, -1, v82
	s_nop 1
	v_cndmask_b32_e32 v78, v130, v78, vcc
	v_cmp_lt_i32_e32 vcc, 31, v82
	v_add_u32_e32 v82, 0x42, v114
	s_nop 0
	v_cndmask_b32_e32 v64, v130, v64, vcc
	v_cmp_lt_i32_e32 vcc, -1, v82
	s_nop 1
	v_cndmask_b32_e32 v79, v130, v79, vcc
	v_cmp_lt_i32_e32 vcc, 31, v82
	v_add_u32_e32 v82, 0x41, v114
	s_nop 0
	v_cndmask_b32_e32 v65, v130, v65, vcc
	v_cmp_lt_i32_e32 vcc, -1, v82
	s_nop 1
	v_cndmask_b32_e32 v80, v130, v80, vcc
	v_cmp_lt_i32_e32 vcc, 31, v82
	v_add_u32_e32 v82, 64, v114
	s_nop 0
	v_cndmask_b32_e32 v66, v130, v66, vcc
	v_cmp_lt_i32_e32 vcc, -1, v82
	s_nop 1
	v_cndmask_b32_e32 v81, v130, v81, vcc
	v_cmp_lt_i32_e32 vcc, 31, v82
	s_nop 1
	v_cndmask_b32_e32 v67, v130, v67, vcc

.LBB0_373:
	ds_read_b128 v[184:187], v115 offset:32768
	ds_read_b128 v[188:191], v115 offset:36864
	ds_read_b128 v[192:195], v116 offset:32768
	ds_read_b128 v[196:199], v116 offset:36864
	ds_read_b128 v[200:203], v117 offset:32768
	ds_read_b128 v[204:207], v117 offset:36864
	ds_read_b128 v[208:211], v118 offset:32768
	ds_read_b128 v[212:215], v118 offset:36864
	ds_read_b128 v[106:109], v113 offset:256
	ds_read_b128 v[140:143], v113 offset:384
	ds_read_b128 v[144:147], v113 offset:288
	ds_read_b128 v[148:151], v113 offset:416
	s_waitcnt lgkmcnt(11)
	v_mfma_f32_32x32x16_bf16 v[68:83], v[184:187], v[96:99], v[36:51]
	s_waitcnt lgkmcnt(10)
	v_mfma_f32_32x32x16_bf16 v[52:67], v[188:191], v[96:99], v[36:51]
	s_waitcnt lgkmcnt(9)
	v_mfma_f32_32x32x16_bf16 v[68:83], v[192:195], v[92:95], v[68:83]
	s_waitcnt lgkmcnt(8)
	v_mfma_f32_32x32x16_bf16 v[52:67], v[196:199], v[92:95], v[52:67]
	s_waitcnt lgkmcnt(7)
	v_mfma_f32_32x32x16_bf16 v[68:83], v[200:203], v[88:91], v[68:83]
	s_waitcnt lgkmcnt(6)
	v_mfma_f32_32x32x16_bf16 v[52:67], v[204:207], v[88:91], v[52:67]
	s_waitcnt lgkmcnt(5)
	v_mfma_f32_32x32x16_bf16 v[68:83], v[208:211], v[84:87], v[68:83]
	s_waitcnt lgkmcnt(4)
	v_mfma_f32_32x32x16_bf16 v[52:67], v[212:215], v[84:87], v[52:67]
	s_nop 9
	s_cmp_le_i32 s29, s28
	s_waitcnt lgkmcnt(3)
	v_sub_f32_e32 v68, v68, v106
	s_waitcnt lgkmcnt(2)
	v_sub_f32_e32 v106, v52, v140
	v_sub_f32_e32 v69, v69, v107
	v_sub_f32_e32 v107, v53, v141
	v_sub_f32_e32 v52, v70, v108
	v_sub_f32_e32 v54, v54, v142
	v_sub_f32_e32 v53, v71, v109
	v_sub_f32_e32 v55, v55, v143
	s_waitcnt lgkmcnt(1)
	v_sub_f32_e32 v70, v72, v144
	s_waitcnt lgkmcnt(0)
	v_sub_f32_e32 v56, v56, v148
	v_sub_f32_e32 v71, v73, v145
	v_sub_f32_e32 v57, v57, v149
	v_sub_f32_e32 v72, v74, v146
	v_sub_f32_e32 v58, v58, v150
	ds_read_b128 v[140:143], v113 offset:320
	v_sub_f32_e32 v73, v75, v147
	ds_read_b128 v[144:147], v113 offset:448
	ds_read_b128 v[152:155], v113 offset:480
	v_sub_f32_e32 v59, v59, v151
	ds_read_b128 v[148:151], v113 offset:352
	s_waitcnt lgkmcnt(3)
	v_sub_f32_e32 v74, v76, v140
	s_waitcnt lgkmcnt(2)
	v_sub_f32_e32 v76, v60, v144
	v_sub_f32_e32 v75, v77, v141
	v_sub_f32_e32 v77, v61, v145
	v_sub_f32_e32 v60, v78, v142
	v_sub_f32_e32 v62, v62, v146
	v_sub_f32_e32 v61, v79, v143
	v_sub_f32_e32 v63, v63, v147
	s_waitcnt lgkmcnt(0)
	v_sub_f32_e32 v78, v80, v148
	v_sub_f32_e32 v64, v64, v152
	v_sub_f32_e32 v79, v81, v149
	v_sub_f32_e32 v65, v65, v153
	v_sub_f32_e32 v80, v82, v150
	v_sub_f32_e32 v66, v66, v154
	v_sub_f32_e32 v81, v83, v151
	v_sub_f32_e32 v67, v67, v155
	s_cbranch_scc1 .LBB0_375
	v_add_u32_e32 v82, 27, v114
	v_cmp_lt_i32_e32 vcc, -1, v82
	s_nop 1
	v_cndmask_b32_e32 v68, v130, v68, vcc
	v_cmp_lt_i32_e32 vcc, 31, v82
	v_add_u32_e32 v82, 26, v114
	s_nop 0
	v_cndmask_b32_e32 v106, v130, v106, vcc
	v_cmp_lt_i32_e32 vcc, -1, v82
	s_nop 1
	v_cndmask_b32_e32 v69, v130, v69, vcc
	v_cmp_lt_i32_e32 vcc, 31, v82
	v_add_u32_e32 v82, 25, v114
	s_nop 0
	v_cndmask_b32_e32 v107, v130, v107, vcc
	v_cmp_lt_i32_e32 vcc, -1, v82
	s_nop 1
	v_cndmask_b32_e32 v52, v130, v52, vcc
	v_cmp_lt_i32_e32 vcc, 31, v82
	v_add_u32_e32 v82, 24, v114
	s_nop 0
	v_cndmask_b32_e32 v54, v130, v54, vcc
	v_cmp_lt_i32_e32 vcc, -1, v82
	s_nop 1
	v_cndmask_b32_e32 v53, v130, v53, vcc
	v_cmp_lt_i32_e32 vcc, 31, v82
	v_add_u32_e32 v82, 19, v114
	s_nop 0
	v_cndmask_b32_e32 v55, v130, v55, vcc
	v_cmp_lt_i32_e32 vcc, -1, v82
	s_nop 1
	v_cndmask_b32_e32 v70, v130, v70, vcc
	v_cmp_lt_i32_e32 vcc, 31, v82
	v_add_u32_e32 v82, 18, v114
	s_nop 0
	v_cndmask_b32_e32 v56, v130, v56, vcc
	v_cmp_lt_i32_e32 vcc, -1, v82
	s_nop 1
	v_cndmask_b32_e32 v71, v130, v71, vcc
	v_cmp_lt_i32_e32 vcc, 31, v82
	v_add_u32_e32 v82, 17, v114
	s_nop 0
	v_cndmask_b32_e32 v57, v130, v57, vcc
	v_cmp_lt_i32_e32 vcc, -1, v82
	s_nop 1
	v_cndmask_b32_e32 v72, v130, v72, vcc
	v_cmp_lt_i32_e32 vcc, 31, v82
	v_add_u32_e32 v82, 16, v114
	s_nop 0
	v_cndmask_b32_e32 v58, v130, v58, vcc
	v_cmp_lt_i32_e32 vcc, -1, v82
	s_nop 1
	v_cndmask_b32_e32 v73, v130, v73, vcc
	v_cmp_lt_i32_e32 vcc, 31, v82
	v_add_u32_e32 v82, 11, v114
	s_nop 0
	v_cndmask_b32_e32 v59, v130, v59, vcc
	v_cmp_lt_i32_e32 vcc, -1, v82
	s_nop 1
	v_cndmask_b32_e32 v74, v130, v74, vcc
	v_cmp_lt_i32_e32 vcc, 31, v82
	v_add_u32_e32 v82, 10, v114
	s_nop 0
	v_cndmask_b32_e32 v76, v130, v76, vcc
	v_cmp_lt_i32_e32 vcc, -1, v82
	s_nop 1
	v_cndmask_b32_e32 v75, v130, v75, vcc
	v_cmp_lt_i32_e32 vcc, 31, v82
	v_add_u32_e32 v82, 9, v114
	s_nop 0
	v_cndmask_b32_e32 v77, v130, v77, vcc
	v_cmp_lt_i32_e32 vcc, -1, v82
	s_nop 1
	v_cndmask_b32_e32 v60, v130, v60, vcc
	v_cmp_lt_i32_e32 vcc, 31, v82
	v_add_u32_e32 v82, 8, v114
	s_nop 0
	v_cndmask_b32_e32 v62, v130, v62, vcc
	v_cmp_lt_i32_e32 vcc, -1, v82
	s_nop 1
	v_cndmask_b32_e32 v61, v130, v61, vcc
	v_cmp_lt_i32_e32 vcc, 31, v82
	v_add_u32_e32 v82, 3, v114
	s_nop 0
	v_cndmask_b32_e32 v63, v130, v63, vcc
	v_cmp_lt_i32_e32 vcc, -1, v82
	s_nop 1
	v_cndmask_b32_e32 v78, v130, v78, vcc
	v_cmp_lt_i32_e32 vcc, 31, v82
	v_add_u32_e32 v82, 2, v114
	s_nop 0
	v_cndmask_b32_e32 v64, v130, v64, vcc
	v_cmp_lt_i32_e32 vcc, -1, v82
	s_nop 1
	v_cndmask_b32_e32 v79, v130, v79, vcc
	v_cmp_lt_i32_e32 vcc, 31, v82
	v_add_u32_e32 v82, 1, v114
	s_nop 0
	v_cndmask_b32_e32 v65, v130, v65, vcc
	v_cmp_lt_i32_e32 vcc, -1, v82
	s_nop 1
	v_cndmask_b32_e32 v80, v130, v80, vcc
	v_cmp_lt_i32_e32 vcc, 31, v82
	s_nop 1
	v_cndmask_b32_e32 v66, v130, v66, vcc
	v_cmp_lt_i32_e32 vcc, -1, v114
	s_nop 1
	v_cndmask_b32_e32 v81, v130, v81, vcc
	v_cmp_lt_i32_e32 vcc, 31, v114
	s_nop 1
	v_cndmask_b32_e32 v67, v130, v67, vcc

.LBB0_1422:
	s_lshl_b32 s0, s87, 6
	s_and_b32 s89, s0, 0x2000
	s_bfe_u32 s3, s87, 0x30004
	s_mul_i32 s0, s89, 0xc00
	s_add_u32 s5, s16, s0
	s_addc_u32 s7, s20, 0
	s_lshl_b32 s97, s3, 7
	s_lshl_b32 s0, s3, 8
	s_add_u32 s0, s5, s0
	s_addc_u32 s1, s7, 0
	s_add_u32 s6, s5, s97
	s_addc_u32 s7, s7, 0
	s_lshl_b32 s5, s89, 12
	s_add_u32 s5, s18, s5
	s_addc_u32 s9, s83, 0
	s_lshl_b32 s3, s3, 9
	s_add_u32 s8, s5, s3
	s_addc_u32 s9, s9, 0
	s_lshl_b32 s3, s89, 7
	s_add_u32 s3, s33, s3
	s_addc_u32 s5, s24, 0
	s_lshl_b32 s10, s87, 8
	s_and_b32 s10, s10, 0xf00
	s_xor_b32 s11, s10, 0x1f00
	v_mov_b32_e32 v187, v182
	s_cmpk_lt_u32 s87, 0x100
	s_cselect_b32 s85, s11, s10
	v_readfirstlane_b32 s82, v187
	s_ashr_i32 s10, s82, 6
	v_and_b32_e32 v98, 63, v187
	v_lshlrev_b32_e32 v62, 4, v98
	s_mul_i32 s12, s10, 0xc00
	v_or_b32_e32 v19, s12, v62
	v_mul_hi_i32 v18, v19, s19
	v_lshrrev_b32_e32 v20, 31, v18
	v_ashrrev_i32_e32 v18, 6, v18
	v_add_u32_e32 v18, v18, v20
	v_mul_i32_i24_e32 v20, 0x180, v18
	v_sub_u32_e32 v19, v19, v20
	v_ashrrev_i32_e32 v20, 4, v19
	v_lshrrev_b32_e32 v21, 1, v18
	v_bitop3_b32 v20, v21, v20, 7 bitop3:0x6c
	v_cmp_lt_i32_e32 vcc, s17, v19
	v_lshlrev_b32_e32 v20, 3, v20
	v_ashrrev_i32_e32 v19, 31, v18
	v_cndmask_b32_e64 v21, 11, 6, vcc
	s_lshl_b32 s11, s10, 5
	v_lshlrev_b64 v[18:19], v21, v[18:19]
	v_add_u32_e32 v21, 0xffffff80, v20
	v_mov_b32_e32 v24, s9
	v_mov_b32_e32 v25, s5
	v_mov_b32_e32 v26, s8
	v_mov_b32_e32 v27, s3
	s_add_i32 s96, s11, s85
	s_mul_i32 s11, s10, 3
	v_cndmask_b32_e32 v20, v20, v21, vcc
	v_cndmask_b32_e32 v23, v24, v25, vcc
	v_cndmask_b32_e32 v22, v26, v27, vcc
	v_ashrrev_i32_e32 v21, 31, v20
	v_lshl_add_u64 v[18:19], v[18:19], 1, v[22:23]
	s_add_i32 s3, s11, 1
	v_lshl_add_u64 v[46:47], v[20:21], 1, v[18:19]
	v_lshl_or_b32 v19, s3, 10, v62
	v_mul_hi_i32 v18, v19, s19
	v_lshrrev_b32_e32 v20, 31, v18
	v_ashrrev_i32_e32 v18, 6, v18
	v_add_u32_e32 v18, v18, v20
	v_mul_i32_i24_e32 v20, 0x180, v18
	v_sub_u32_e32 v19, v19, v20
	v_ashrrev_i32_e32 v20, 4, v19
	v_lshrrev_b32_e32 v21, 1, v18
	v_cndmask_b32_e32 v76, v1, v183, vcc
	v_bitop3_b32 v20, v21, v20, 7 bitop3:0x6c
	v_cmp_lt_i32_e32 vcc, s17, v19
	v_lshlrev_b32_e32 v20, 3, v20
	v_ashrrev_i32_e32 v19, 31, v18
	v_cndmask_b32_e64 v21, 11, 6, vcc
	v_lshlrev_b64 v[18:19], v21, v[18:19]
	v_add_u32_e32 v21, 0xffffff80, v20
	v_cndmask_b32_e32 v20, v20, v21, vcc
	v_cndmask_b32_e32 v23, v24, v25, vcc
	v_cndmask_b32_e32 v22, v26, v27, vcc
	v_ashrrev_i32_e32 v21, 31, v20
	v_lshl_add_u64 v[18:19], v[18:19], 1, v[22:23]
	s_add_i32 s5, s11, 2
	v_lshl_add_u64 v[48:49], v[20:21], 1, v[18:19]
	v_lshl_or_b32 v19, s5, 10, v62
	v_mul_hi_i32 v18, v19, s19
	v_lshrrev_b32_e32 v20, 31, v18
	v_ashrrev_i32_e32 v18, 6, v18
	v_add_u32_e32 v18, v18, v20
	v_mul_i32_i24_e32 v20, 0x180, v18
	v_sub_u32_e32 v19, v19, v20
	v_ashrrev_i32_e32 v20, 4, v19
	v_lshrrev_b32_e32 v21, 1, v18
	v_cndmask_b32_e32 v77, v1, v183, vcc
	v_bitop3_b32 v20, v21, v20, 7 bitop3:0x6c
	v_cmp_lt_i32_e32 vcc, s17, v19
	v_lshlrev_b32_e32 v20, 3, v20
	v_ashrrev_i32_e32 v19, 31, v18
	v_cndmask_b32_e64 v21, 11, 6, vcc
	v_lshlrev_b64 v[18:19], v21, v[18:19]
	v_add_u32_e32 v21, 0xffffff80, v20
	v_cndmask_b32_e32 v20, v20, v21, vcc
	v_cndmask_b32_e32 v23, v24, v25, vcc
	v_cndmask_b32_e32 v22, v26, v27, vcc
	v_ashrrev_i32_e32 v21, 31, v20
	v_lshl_add_u64 v[18:19], v[18:19], 1, v[22:23]
	s_lshl_b32 s86, s10, 11
	v_lshl_add_u64 v[56:57], v[20:21], 1, v[18:19]
	s_ashr_i32 s12, s86, 8
	v_lshrrev_b32_e32 v19, 1, v187
	v_bfe_u32 v18, v187, 2, 2
	s_and_b32 s13, s12, -16
	v_and_b32_e32 v19, 8, v19
	s_lshr_b32 s12, s12, 1
	v_or3_b32 v18, v19, v18, s13
	v_lshlrev_b32_e32 v60, 3, v98
	v_and_or_b32 v18, s12, 4, v18
	v_and_b32_e32 v61, 24, v60
	v_and_b32_e32 v22, 32, v187
	v_ashrrev_i32_e32 v19, 31, v18
	v_lshlrev_b64 v[18:19], 12, v[18:19]
	v_or_b32_e32 v20, v61, v22
	v_lshl_add_u64 v[18:19], s[8:9], 0, v[18:19]
	v_lshlrev_b32_e32 v162, 1, v20
	v_lshl_add_u64 v[54:55], v[18:19], 0, v[162:163]
	s_mov_b64 s[8:9], 0x100
	s_lshl_b32 s74, s11, 10
	v_lshl_add_u64 v[50:51], v[54:55], 0, s[8:9]
	s_mov_b64 s[8:9], 0x180
	s_cmp_lg_u32 0, -1
	v_lshl_add_u64 v[18:19], v[54:55], 0, s[8:9]
	s_cselect_b32 s8, 0, 0
	s_add_i32 s9, s8, 0x8000
	s_lshl_b32 s75, s3, 10
	s_add_i32 s11, s74, s9
	s_mov_b32 s12, m0
	s_mov_b32 m0, s11
	s_nop 0
	global_load_lds_dwordx4 v[46:47], off
	s_mov_b32 m0, s12
	s_add_i32 s3, s75, s9
	s_lshl_b32 s5, s5, 10
	s_mov_b32 s11, m0
	s_mov_b32 m0, s3
	s_nop 0
	global_load_lds_dwordx4 v[48:49], off
	s_mov_b32 m0, s11
	s_add_i32 s3, s5, s9
	s_mov_b32 s9, m0
	s_mov_b32 m0, s3
	s_nop 0
	global_load_lds_dwordx4 v[56:57], off
	s_mov_b32 m0, s9
	s_add_i32 s3, s86, s8
	v_and_b32_e32 v189, 31, v187
	s_mov_b32 s9, m0
	s_mov_b32 m0, s3
	s_nop 0
	global_load_lds_dwordx4 v[50:51], off
	s_mov_b32 m0, s9
	s_or_b32 s3, s86, 0x400
	v_bfe_u32 v63, v187, 5, 1
	v_or_b32_e32 v52, s96, v189
	s_add_i32 s9, s3, s8
	s_mov_b32 s11, m0
	s_mov_b32 m0, s9
	s_nop 0
	global_load_lds_dwordx4 v[18:19], off
	s_mov_b32 m0, s11
	v_mov_b64_e32 v[18:19], s[6:7]
	v_ashrrev_i32_e32 v53, 31, v52
	v_lshlrev_b32_e32 v58, 4, v63
	v_mov_b32_e32 v59, v163
	v_mad_i64_i32 v[18:19], s[6:7], v52, s27, v[18:19]
	v_lshl_add_u64 v[34:35], v[18:19], 0, v[58:59]
	v_lshlrev_b64 v[68:69], 8, v[52:53]
	global_load_dwordx4 v[18:21], v[34:35], off offset:2048
	v_or_b32_e32 v68, v68, v22
	v_lshl_add_u64 v[26:27], s[94:95], 0, v[68:69]
	v_mov_b64_e32 v[234:235], v[26:27]
	global_load_dwordx4 v[22:25], v[26:27], off
	s_nop 0
	global_load_dwordx4 v[26:29], v[26:27], off offset:16
	v_mov_b64_e32 v[30:31], s[0:1]
	v_mad_i64_i32 v[30:31], s[0:1], v52, s27, v[30:31]
	v_lshl_add_u64 v[30:31], v[30:31], 0, v[58:59]
	global_load_dwordx4 v[158:161], v[30:31], off
	global_load_dwordx4 v[154:157], v[30:31], off offset:32
	global_load_dwordx4 v[150:153], v[30:31], off offset:64
	global_load_dwordx4 v[146:149], v[30:31], off offset:96
	global_load_dwordx4 v[142:145], v[30:31], off offset:128
	global_load_dwordx4 v[138:141], v[30:31], off offset:160
	global_load_dwordx4 v[134:137], v[30:31], off offset:192
	global_load_dwordx4 v[130:133], v[30:31], off offset:224
	s_nop 0
	global_load_dwordx4 v[30:33], v[34:35], off offset:2080
	global_load_dwordx4 v[64:67], v[34:35], off offset:2112
	global_load_dwordx4 v[38:41], v[34:35], off offset:2144
	global_load_dwordx4 v[238:241], v[234:235], off offset:64
	global_load_dwordx4 v[242:245], v[234:235], off offset:80
	global_load_dwordx4 v[246:249], v[234:235], off offset:128
	global_load_dwordx4 v[250:253], v[234:235], off offset:144
	global_load_dwordx4 v[226:229], v[234:235], off offset:192
	global_load_dwordx4 v[230:233], v[234:235], off offset:208
	s_movk_i32 s9, 0x180
	v_cndmask_b32_e32 v78, v1, v183, vcc
	v_mov_b32_e32 v165, v163
	s_mov_b64 s[0:1], 0x40100
	s_mov_b64 s[6:7], 0x40180
	v_lshlrev_b32_e32 v186, 2, v63
	v_mad_u32_u24 v59, v189, s9, 0
	s_lshl_b32 s9, s10, 12
	v_lshlrev_b32_e32 v162, 1, v76
	v_lshlrev_b32_e32 v164, 1, v77
	v_sub_u32_e32 v192, v52, v186
	s_add_i32 s9, s9, 0
	v_lshlrev_b32_e32 v166, 1, v78
	v_lshl_add_u64 v[76:77], v[54:55], 0, s[0:1]
	v_lshl_add_u64 v[78:79], v[54:55], 0, s[6:7]
	v_lshl_add_u64 v[54:55], v[48:49], 0, v[164:165]
	s_add_i32 s9, s9, 0x14800
	v_add_u32_e32 v193, s9, v62
	s_add_i32 s10, s8, 0xe000
	s_add_i32 s11, s74, s10
	v_mov_b32_e32 v167, v163
	s_add_i32 s12, s75, s10
	s_addk_i32 s8, 0x4000
	s_add_i32 s10, s5, s10
	v_lshl_add_u64 v[56:57], v[56:57], 0, v[166:167]
	s_add_i32 s13, s86, s8
	s_waitcnt vmcnt(19)
	v_lshlrev_b32_e32 v34, 16, v18
	v_and_b32_e32 v35, 0xffff0000, v18
	s_waitcnt vmcnt(18)
	v_pk_mul_f32 v[36:37], v[22:23], v[34:35]
	v_pk_mul_f32 v[22:23], v[22:23], v[34:35] op_sel:[0,1] op_sel_hi:[1,0]
	v_sub_f32_e32 v18, v36, v37
	v_add_f32_e32 v22, v22, v23
	v_cvt_pk_bf16_f32 v34, v18, v22
	v_lshlrev_b32_e32 v18, 16, v19
	v_and_b32_e32 v19, 0xffff0000, v19
	v_pk_mul_f32 v[22:23], v[24:25], v[18:19]
	v_pk_mul_f32 v[18:19], v[24:25], v[18:19] op_sel:[0,1] op_sel_hi:[1,0]
	v_sub_f32_e32 v22, v22, v23
	v_add_f32_e32 v18, v18, v19
	v_cvt_pk_bf16_f32 v35, v22, v18
	v_lshlrev_b32_e32 v18, 16, v20
	v_and_b32_e32 v19, 0xffff0000, v20
	s_waitcnt vmcnt(17)
	v_pk_mul_f32 v[22:23], v[26:27], v[18:19]
	v_pk_mul_f32 v[18:19], v[26:27], v[18:19] op_sel:[0,1] op_sel_hi:[1,0]
	v_sub_f32_e32 v20, v22, v23
	v_add_f32_e32 v18, v18, v19
	v_cvt_pk_bf16_f32 v36, v20, v18
	v_lshlrev_b32_e32 v18, 16, v21
	v_and_b32_e32 v19, 0xffff0000, v21
	v_pk_mul_f32 v[20:21], v[28:29], v[18:19]
	v_pk_mul_f32 v[18:19], v[28:29], v[18:19] op_sel:[0,1] op_sel_hi:[1,0]
	v_sub_f32_e32 v20, v20, v21
	v_add_f32_e32 v18, v18, v19
	v_cvt_pk_bf16_f32 v37, v20, v18
	v_or_b32_e32 v18, 64, v68
	v_mov_b32_e32 v19, v69
	v_lshl_add_u64 v[22:23], s[94:95], 0, v[18:19]
	s_waitcnt vmcnt(8)
	v_lshlrev_b32_e32 v26, 16, v30
	v_and_b32_e32 v27, 0xffff0000, v30
	s_waitcnt vmcnt(7)
	v_lshlrev_b32_e32 v30, 16, v65
	s_waitcnt vmcnt(6)
	v_lshlrev_b32_e32 v48, 16, v40
	v_and_b32_e32 v49, 0xffff0000, v40
	v_lshlrev_b32_e32 v40, 16, v41
	v_and_b32_e32 v41, 0xffff0000, v41
	s_waitcnt vmcnt(5)
	v_pk_mul_f32 v[28:29], v[238:239], v[26:27]
	v_pk_mul_f32 v[18:19], v[238:239], v[26:27] op_sel:[0,1] op_sel_hi:[1,0]
	v_sub_f32_e32 v28, v28, v29
	v_add_f32_e32 v18, v18, v19
	v_cvt_pk_bf16_f32 v42, v28, v18
	v_lshlrev_b32_e32 v18, 16, v31
	v_and_b32_e32 v19, 0xffff0000, v31
	v_pk_mul_f32 v[26:27], v[240:241], v[18:19]
	v_pk_mul_f32 v[18:19], v[240:241], v[18:19] op_sel:[0,1] op_sel_hi:[1,0]
	v_sub_f32_e32 v26, v26, v27
	v_add_f32_e32 v18, v18, v19
	v_cvt_pk_bf16_f32 v43, v26, v18
	v_lshlrev_b32_e32 v18, 16, v32
	v_and_b32_e32 v19, 0xffff0000, v32
	s_waitcnt vmcnt(4)
	v_pk_mul_f32 v[20:21], v[242:243], v[18:19]
	v_pk_mul_f32 v[18:19], v[242:243], v[18:19] op_sel:[0,1] op_sel_hi:[1,0]
	v_sub_f32_e32 v20, v20, v21
	v_add_f32_e32 v18, v18, v19
	v_cvt_pk_bf16_f32 v44, v20, v18
	v_lshlrev_b32_e32 v18, 16, v33
	v_and_b32_e32 v19, 0xffff0000, v33
	v_pk_mul_f32 v[20:21], v[244:245], v[18:19]
	v_pk_mul_f32 v[18:19], v[244:245], v[18:19] op_sel:[0,1] op_sel_hi:[1,0]
	v_sub_f32_e32 v20, v20, v21
	v_add_f32_e32 v18, v18, v19
	v_cvt_pk_bf16_f32 v45, v20, v18
	v_or_b32_e32 v18, 0x80, v68
	v_mov_b32_e32 v19, v69
	v_lshl_add_u64 v[22:23], s[94:95], 0, v[18:19]
	v_or_b32_e32 v68, 0xc0, v68
	v_lshlrev_b32_e32 v28, 16, v64
	v_and_b32_e32 v29, 0xffff0000, v64
	v_and_b32_e32 v31, 0xffff0000, v65
	v_lshlrev_b32_e32 v32, 16, v66
	v_and_b32_e32 v33, 0xffff0000, v66
	v_lshlrev_b32_e32 v64, 16, v67
	v_and_b32_e32 v65, 0xffff0000, v67
	v_lshl_add_u64 v[26:27], s[94:95], 0, v[68:69]
	s_waitcnt vmcnt(3)
	v_pk_mul_f32 v[66:67], v[246:247], v[28:29]
	v_pk_mul_f32 v[18:19], v[246:247], v[28:29] op_sel:[0,1] op_sel_hi:[1,0]
	v_pk_mul_f32 v[28:29], v[248:249], v[30:31]
	v_pk_mul_f32 v[20:21], v[248:249], v[30:31] op_sel:[0,1] op_sel_hi:[1,0]
	s_waitcnt vmcnt(2)
	v_pk_mul_f32 v[30:31], v[250:251], v[32:33]
	v_pk_mul_f32 v[22:23], v[250:251], v[32:33] op_sel:[0,1] op_sel_hi:[1,0]
	v_pk_mul_f32 v[32:33], v[252:253], v[64:65]
	v_pk_mul_f32 v[24:25], v[252:253], v[64:65] op_sel:[0,1] op_sel_hi:[1,0]
	v_sub_f32_e32 v53, v66, v67
	v_add_f32_e32 v18, v18, v19
	v_sub_f32_e32 v19, v28, v29
	v_add_f32_e32 v20, v20, v21
	v_sub_f32_e32 v21, v30, v31
	v_add_f32_e32 v22, v22, v23
	v_sub_f32_e32 v23, v32, v33
	v_add_f32_e32 v24, v24, v25
	v_cvt_pk_bf16_f32 v64, v53, v18
	v_cvt_pk_bf16_f32 v65, v19, v20
	v_cvt_pk_bf16_f32 v66, v21, v22
	v_cvt_pk_bf16_f32 v67, v23, v24
	v_lshlrev_b32_e32 v53, 3, v187
	v_and_b32_e32 v63, 0x70, v53
	v_lshl_add_u64 v[52:53], v[46:47], 0, v[162:163]
	v_lshlrev_b32_e32 v46, 16, v38
	v_and_b32_e32 v47, 0xffff0000, v38
	v_lshlrev_b32_e32 v38, 16, v39
	v_and_b32_e32 v39, 0xffff0000, v39
	v_mov_b64_e32 v[32:33], v[16:17]
	v_mov_b64_e32 v[30:31], v[14:15]
	v_mov_b64_e32 v[28:29], v[12:13]
	v_mov_b64_e32 v[26:27], v[10:11]
	v_mov_b64_e32 v[24:25], v[8:9]
	v_mov_b64_e32 v[22:23], v[6:7]
	v_mov_b64_e32 v[20:21], v[4:5]
	v_mov_b64_e32 v[18:19], v[2:3]
	s_waitcnt vmcnt(1)
	v_pk_mul_f32 v[80:81], v[226:227], v[46:47]
	v_pk_mul_f32 v[46:47], v[226:227], v[46:47] op_sel:[0,1] op_sel_hi:[1,0]
	v_pk_mul_f32 v[68:69], v[228:229], v[38:39]
	v_pk_mul_f32 v[38:39], v[228:229], v[38:39] op_sel:[0,1] op_sel_hi:[1,0]
	s_waitcnt vmcnt(0)
	v_pk_mul_f32 v[70:71], v[230:231], v[48:49]
	v_pk_mul_f32 v[48:49], v[230:231], v[48:49] op_sel:[0,1] op_sel_hi:[1,0]
	v_pk_mul_f32 v[72:73], v[232:233], v[40:41]
	v_pk_mul_f32 v[40:41], v[232:233], v[40:41] op_sel:[0,1] op_sel_hi:[1,0]
	v_add_f32_e32 v39, v38, v39
	v_add_f32_e32 v41, v40, v41
	v_sub_f32_e32 v74, v80, v81
	v_add_f32_e32 v46, v46, v47
	v_sub_f32_e32 v47, v68, v69
	v_sub_f32_e32 v68, v70, v71
	v_add_f32_e32 v48, v48, v49
	v_sub_f32_e32 v49, v72, v73
	v_cvt_pk_bf16_f32 v38, v74, v46
	v_cvt_pk_bf16_f32 v39, v47, v39
	v_cvt_pk_bf16_f32 v40, v68, v48
	v_cvt_pk_bf16_f32 v41, v49, v41
	ds_write_b128 v193, v[34:37]
	ds_write_b128 v193, v[42:45] offset:1024
	ds_write_b128 v193, v[64:67] offset:2048
	ds_write_b128 v193, v[38:41] offset:3072
	s_waitcnt vmcnt(0)
	s_waitcnt lgkmcnt(0)
	s_barrier
	s_mov_b32 s0, m0
	s_mov_b32 m0, s11
	s_nop 0
	global_load_lds_dwordx4 v[52:53], off
	s_mov_b32 m0, s0
	s_nop 0
	s_mov_b32 s0, m0
	s_mov_b32 m0, s12
	s_nop 0
	global_load_lds_dwordx4 v[54:55], off
	s_mov_b32 m0, s0
	s_nop 0
	s_mov_b32 s0, m0
	s_mov_b32 m0, s10
	s_nop 0
	global_load_lds_dwordx4 v[56:57], off
	s_mov_b32 m0, s0
	s_nop 0
	s_mov_b32 s0, m0
	s_mov_b32 m0, s13
	s_nop 0
	global_load_lds_dwordx4 v[76:77], off
	s_mov_b32 m0, s0
	s_add_i32 s0, s3, s8
	s_mov_b32 s1, m0
	s_mov_b32 m0, s0
	s_nop 0
	global_load_lds_dwordx4 v[78:79], off
	s_mov_b32 m0, s1
	v_xad_u32 v194, v58, v63, v59
	ds_read_b128 v[64:67], v194 offset:32768
	ds_read_b128 v[68:71], v194 offset:45056
	s_waitcnt lgkmcnt(1)
	v_mfma_f32_32x32x16_bf16 v[34:49], v[64:67], v[158:161], v[18:33]
	v_or_b32_e32 v64, 32, v58
	v_xad_u32 v195, v64, v63, v59
	s_waitcnt lgkmcnt(0)
	v_mfma_f32_32x32x16_bf16 v[18:33], v[68:71], v[158:161], v[18:33]
	ds_read_b128 v[64:67], v195 offset:32768
	ds_read_b128 v[68:71], v195 offset:45056
	s_waitcnt lgkmcnt(1)
	v_mfma_f32_32x32x16_bf16 v[34:49], v[64:67], v[154:157], v[34:49]
	s_waitcnt lgkmcnt(0)
	v_mfma_f32_32x32x16_bf16 v[18:33], v[68:71], v[154:157], v[18:33]
	v_or_b32_e32 v64, 64, v58
	v_xad_u32 v196, v64, v63, v59
	ds_read_b128 v[64:67], v196 offset:32768
	ds_read_b128 v[68:71], v196 offset:45056
	v_or_b32_e32 v58, 0x60, v58
	v_xad_u32 v197, v58, v63, v59
	s_waitcnt lgkmcnt(1)
	v_mfma_f32_32x32x16_bf16 v[34:49], v[64:67], v[150:153], v[34:49]
	s_waitcnt lgkmcnt(0)
	v_mfma_f32_32x32x16_bf16 v[18:33], v[68:71], v[150:153], v[18:33]
	ds_read_b128 v[64:67], v197 offset:32768
	ds_read_b128 v[68:71], v197 offset:45056
	s_waitcnt lgkmcnt(1)
	v_mfma_f32_32x32x16_bf16 v[34:49], v[64:67], v[146:149], v[34:49]
	s_waitcnt lgkmcnt(0)
	v_mfma_f32_32x32x16_bf16 v[18:33], v[68:71], v[146:149], v[18:33]
	ds_read_b128 v[64:67], v194 offset:32896
	ds_read_b128 v[68:71], v194 offset:45184
	s_waitcnt lgkmcnt(1)
	v_mfma_f32_32x32x16_bf16 v[34:49], v[64:67], v[142:145], v[34:49]
	s_waitcnt lgkmcnt(0)
	v_mfma_f32_32x32x16_bf16 v[18:33], v[68:71], v[142:145], v[18:33]
	ds_read_b128 v[64:67], v195 offset:32896
	ds_read_b128 v[68:71], v195 offset:45184
	s_waitcnt lgkmcnt(1)
	v_mfma_f32_32x32x16_bf16 v[34:49], v[64:67], v[138:141], v[34:49]
	s_waitcnt lgkmcnt(0)
	v_mfma_f32_32x32x16_bf16 v[18:33], v[68:71], v[138:141], v[18:33]
	ds_read_b128 v[64:67], v196 offset:32896
	ds_read_b128 v[68:71], v196 offset:45184
	s_waitcnt lgkmcnt(1)
	v_mfma_f32_32x32x16_bf16 v[34:49], v[64:67], v[134:137], v[34:49]
	s_waitcnt lgkmcnt(0)
	v_mfma_f32_32x32x16_bf16 v[18:33], v[68:71], v[134:137], v[18:33]
	ds_read_b128 v[64:67], v197 offset:32896
	ds_read_b128 v[68:71], v197 offset:45184
	s_waitcnt lgkmcnt(1)
	v_mfma_f32_32x32x16_bf16 v[34:49], v[64:67], v[130:133], v[34:49]
	s_waitcnt lgkmcnt(0)
	v_mfma_f32_32x32x16_bf16 v[18:33], v[68:71], v[130:133], v[18:33]
	ds_read_b128 v[64:67], v194 offset:33024
	ds_read_b128 v[68:71], v193
	ds_read_b128 v[72:75], v193 offset:1024
	ds_read_b128 v[76:79], v194 offset:45312
	s_waitcnt lgkmcnt(2)
	v_mfma_f32_32x32x16_bf16 v[34:49], v[64:67], v[68:71], v[34:49]
	s_waitcnt lgkmcnt(0)
	v_mfma_f32_32x32x16_bf16 v[18:33], v[76:79], v[68:71], v[18:33]
	ds_read_b128 v[64:67], v195 offset:33024
	ds_read_b128 v[68:71], v195 offset:45312
	s_waitcnt lgkmcnt(1)
	v_mfma_f32_32x32x16_bf16 v[34:49], v[64:67], v[72:75], v[34:49]
	s_waitcnt lgkmcnt(0)
	v_mfma_f32_32x32x16_bf16 v[18:33], v[68:71], v[72:75], v[18:33]
	ds_read_b128 v[64:67], v196 offset:33024
	ds_read_b128 v[68:71], v193 offset:2048
	ds_read_b128 v[72:75], v193 offset:3072
	ds_read_b128 v[76:79], v196 offset:45312
	s_waitcnt lgkmcnt(2)
	v_mfma_f32_32x32x16_bf16 v[34:49], v[64:67], v[68:71], v[34:49]
	s_waitcnt lgkmcnt(0)
	v_mfma_f32_32x32x16_bf16 v[18:33], v[76:79], v[68:71], v[18:33]
	ds_read_b128 v[64:67], v197 offset:33024
	ds_read_b128 v[68:71], v197 offset:45312
	s_waitcnt lgkmcnt(1)
	v_mfma_f32_32x32x16_bf16 v[34:49], v[64:67], v[72:75], v[34:49]
	s_waitcnt lgkmcnt(0)
	v_mfma_f32_32x32x16_bf16 v[18:33], v[68:71], v[72:75], v[18:33]
	s_cmp_gt_i32 s96, 62
	s_cbranch_scc1 .LBB0_1424
	v_cmp_gt_i32_e64 s[64:65], 26, v192
	v_cmp_gt_i32_e64 s[66:67], 27, v192
	v_cmp_gt_i32_e64 s[62:63], 25, v192
	s_and_b64 s[64:65], s[66:67], s[64:65]
	v_cmp_gt_i32_e64 s[60:61], 24, v192
	s_and_b64 s[62:63], s[64:65], s[62:63]
	v_cmp_gt_i32_e64 s[58:59], 19, v192
	s_and_b64 s[60:61], s[62:63], s[60:61]
	v_cmp_gt_i32_e64 s[56:57], 18, v192
	s_and_b64 s[58:59], s[60:61], s[58:59]
	v_cmp_gt_i32_e64 s[54:55], 17, v192
	s_and_b64 s[56:57], s[58:59], s[56:57]
	v_cmp_gt_i32_e64 s[52:53], 16, v192
	s_and_b64 s[54:55], s[56:57], s[54:55]
	v_cmp_gt_i32_e64 s[50:51], 11, v192
	s_and_b64 s[52:53], s[54:55], s[52:53]
	v_cmp_gt_i32_e64 s[48:49], 10, v192
	s_and_b64 s[50:51], s[52:53], s[50:51]
	v_cmp_gt_i32_e64 s[46:47], 9, v192
	s_and_b64 s[48:49], s[50:51], s[48:49]
	v_cmp_gt_i32_e64 s[44:45], 8, v192
	s_and_b64 s[46:47], s[48:49], s[46:47]
	v_cmp_gt_i32_e64 s[42:43], 3, v192
	s_and_b64 s[44:45], s[46:47], s[44:45]
	v_cmp_gt_i32_e64 s[40:41], 2, v192
	s_and_b64 s[42:43], s[44:45], s[42:43]
	v_cmp_gt_i32_e64 s[38:39], 1, v192
	s_and_b64 s[40:41], s[42:43], s[40:41]
	v_cmp_gt_i32_e64 s[36:37], 0, v192
	s_and_b64 s[38:39], s[40:41], s[38:39]
	s_and_b64 s[36:37], s[38:39], s[36:37]
	v_cmp_gt_i32_e64 s[34:35], 58, v192
	v_cndmask_b32_e64 v34, v34, v185, s[36:37]
	v_cmp_gt_i32_e64 s[36:37], 59, v192
	v_cmp_gt_i32_e64 s[30:31], 57, v192
	s_and_b64 s[34:35], s[36:37], s[34:35]
	v_cmp_gt_i32_e64 s[28:29], 56, v192
	s_and_b64 s[30:31], s[34:35], s[30:31]
	v_cmp_gt_i32_e64 s[0:1], 32, v192
	s_mov_b64 s[92:93], s[22:23]
	s_mov_b64 s[22:23], s[72:73]
	s_mov_b32 s72, s84
	s_mov_b32 s84, s4
	s_mov_b32 s4, s26
	v_cmp_gt_i32_e64 s[26:27], 51, v192
	s_and_b64 s[28:29], s[30:31], s[28:29]
	v_writelane_b32 v236, s0, 17
	s_mov_b32 s21, s24
	v_cmp_gt_i32_e64 s[24:25], 50, v192
	s_and_b64 s[26:27], s[28:29], s[26:27]
	v_writelane_b32 v236, s1, 18
	v_cmp_gt_i32_e64 s[0:1], 49, v192
	s_and_b64 s[24:25], s[26:27], s[24:25]
	v_cmp_gt_i32_e32 vcc, 48, v192
	s_and_b64 s[0:1], s[24:25], s[0:1]
	v_cmp_gt_i32_e64 s[90:91], 43, v192
	v_cndmask_b32_e64 v27, v27, v185, s[0:1]
	s_and_b64 s[0:1], s[0:1], vcc
	v_cmp_gt_i32_e64 s[80:81], 42, v192
	v_cndmask_b32_e64 v26, v26, v185, s[0:1]
	s_and_b64 s[0:1], s[0:1], s[90:91]
	v_cmp_gt_i32_e64 s[14:15], 41, v192
	v_cndmask_b32_e64 v25, v25, v185, s[0:1]
	s_and_b64 s[0:1], s[0:1], s[80:81]
	v_cmp_gt_i32_e64 s[12:13], 40, v192
	v_cndmask_b32_e64 v24, v24, v185, s[0:1]
	s_and_b64 s[0:1], s[0:1], s[14:15]
	v_cmp_gt_i32_e64 s[10:11], 35, v192
	v_cndmask_b32_e64 v23, v23, v185, s[0:1]
	s_and_b64 s[0:1], s[0:1], s[12:13]
	v_cmp_gt_i32_e64 s[8:9], 34, v192
	v_cndmask_b32_e64 v22, v22, v185, s[0:1]
	s_and_b64 s[0:1], s[0:1], s[10:11]
	v_cmp_gt_i32_e64 s[6:7], 33, v192
	v_cndmask_b32_e64 v21, v21, v185, s[0:1]
	s_and_b64 s[0:1], s[0:1], s[8:9]
	v_cndmask_b32_e64 v20, v20, v185, s[0:1]
	s_and_b64 s[0:1], s[0:1], s[6:7]
	v_readlane_b32 s6, v236, 17
	v_readlane_b32 s7, v236, 18
	s_and_b64 vcc, s[0:1], s[6:7]
	v_cndmask_b32_e64 v49, v49, v185, s[66:67]
	v_cndmask_b32_e64 v48, v48, v185, s[64:65]
	v_cndmask_b32_e64 v47, v47, v185, s[62:63]
	v_cndmask_b32_e64 v46, v46, v185, s[60:61]
	v_cndmask_b32_e64 v45, v45, v185, s[58:59]
	v_cndmask_b32_e64 v44, v44, v185, s[56:57]
	v_cndmask_b32_e64 v43, v43, v185, s[54:55]
	v_cndmask_b32_e64 v42, v42, v185, s[52:53]
	v_cndmask_b32_e64 v41, v41, v185, s[50:51]
	v_cndmask_b32_e64 v40, v40, v185, s[48:49]
	v_cndmask_b32_e64 v39, v39, v185, s[46:47]
	v_cndmask_b32_e64 v38, v38, v185, s[44:45]
	v_cndmask_b32_e64 v37, v37, v185, s[42:43]
	v_cndmask_b32_e64 v36, v36, v185, s[40:41]
	v_cndmask_b32_e64 v35, v35, v185, s[38:39]
	v_cndmask_b32_e64 v33, v33, v185, s[36:37]
	v_cndmask_b32_e64 v32, v32, v185, s[34:35]
	v_cndmask_b32_e64 v31, v31, v185, s[30:31]
	s_mov_b64 s[30:31], 0x80000
	v_cndmask_b32_e64 v30, v30, v185, s[28:29]
	v_cndmask_b32_e64 v29, v29, v185, s[26:27]
	s_movk_i32 s27, 0xc00
	s_mov_b32 s26, s4
	s_mov_b32 s4, s84
	v_cndmask_b32_e64 v28, v28, v185, s[24:25]
	s_mov_b32 s24, s21
	s_mov_b32 s84, s72
	s_mov_b64 s[72:73], s[22:23]
	s_mov_b64 s[22:23], s[92:93]
	v_cndmask_b32_e64 v19, v19, v185, s[0:1]
	v_cndmask_b32_e32 v18, v18, v185, vcc
